# baseline (speedup 1.0000x reference)
.LBB0_22:
	v_and_b32_e32 v6, 0x1800, v11
	v_add_u32_e32 v6, 0xfffff800, v6
	v_cmp_gt_u32_e32 vcc, s0, v11
	s_nop 1
	v_cndmask_b32_e64 v6, v6, 0, vcc
	v_cndmask_b32_e32 v13, v5, v8, vcc
	v_cndmask_b32_e32 v12, v9, v10, vcc
	v_and_or_b32 v6, v11, s1, v6
	v_lshl_add_u64 v[12:13], v[6:7], 2, v[12:13]
	global_load_dword v6, v[12:13], off
	v_add_u32_e32 v12, 0x200, v11
	v_cmp_lt_u32_e32 vcc, s2, v11
	v_mov_b32_e32 v11, v12
	s_or_b64 s[4:5], vcc, s[4:5]
	s_waitcnt vmcnt(0)
	v_mul_f32_e32 v12, 0xbfb8aa3b, v6
	v_exp_f32_e32 v12, v12
	s_nop 0
	v_add_f32_e32 v12, 1.0, v12
	v_div_scale_f32 v13, s[6:7], v12, v12, v6
	v_rcp_f32_e32 v14, v13
	v_div_scale_f32 v15, vcc, v6, v12, v6
	v_fma_f32 v16, -v13, v14, 1.0
	v_fmac_f32_e32 v14, v16, v14
	v_mul_f32_e32 v16, v15, v14
	v_fma_f32 v17, -v13, v16, v15
	v_fmac_f32_e32 v16, v17, v14
	v_fma_f32 v13, -v13, v16, v15
	v_div_fmas_f32 v13, v13, v14, v16
	v_div_fixup_f32 v6, v13, v12, v6
	ds_write_b32 v3, v6
	v_add_u32_e32 v3, 0x800, v3
	s_andn2_b64 exec, exec, s[4:5]
	s_cbranch_execnz .LBB0_22
	s_or_b64 exec, exec, s[4:5]
	v_readfirstlane_b32 s1, v4
	v_readfirstlane_b32 s0, v2
	s_waitcnt lgkmcnt(0)
	v_writelane_b32 v255, s1, 6
	s_barrier
	v_readlane_b32 s1, v255, 0
	s_cmpk_gt_i32 s1, 0x2885
	s_cbranch_scc1 .LBB0_89
	v_add_u32_e32 v2, 0x200, v190
	v_lshrrev_b32_e32 v76, 6, v2
	v_add_u32_e32 v2, 0x600, v190
	v_lshrrev_b32_e32 v78, 6, v2
	v_add_u32_e32 v2, 0xa00, v190
	v_lshrrev_b32_e32 v80, 6, v2
	v_add_u32_e32 v2, 0xe00, v190
	v_lshrrev_b32_e32 v63, 6, v190
	v_lshrrev_b32_e32 v82, 6, v2
	s_movk_i32 s1, 0x404
	v_mov_b32_e32 v2, 0x4040
	v_mad_u32_u24 v31, v63, s1, v2
	v_mov_b32_e32 v2, 0x8080
	v_mad_u32_u24 v33, v63, s1, v2
	v_mov_b32_e32 v2, 0xc0c0
	v_mad_u32_u24 v35, v63, s1, v2
	v_lshlrev_b32_e32 v2, 3, v190
	v_lshrrev_b32_e32 v83, 3, v190
	v_and_b32_e32 v2, 56, v2
	v_mul_u32_u24_e32 v4, 0x404, v2
	v_lshlrev_b32_e32 v5, 2, v83
	v_add3_u32 v84, 0, v4, v5
	v_and_b32_e32 v4, 15, v190
	v_and_b32_e32 v6, 31, v190
	s_mov_b32 s4, 0xbd000000
	v_cvt_f32_ubyte0_e32 v5, v4
	v_cvt_f32_ubyte0_e32 v4, v6
	s_mov_b32 s5, 0xbd800000
	v_pk_mul_f32 v[4:5], v[4:5], s[4:5]
	v_mov_b32_e32 v20, 0x461c4000
	v_cmp_eq_f32_e32 vcc, 0, v5
	s_mov_b32 s1, 0x3f2aaaab
	v_mov_b32_e32 v22, 0x3e91f4c4
	v_cndmask_b32_e64 v16, v20, 1.0, vcc
	v_frexp_mant_f32_e32 v6, v16
	v_cmp_gt_f32_e64 s[4:5], s1, v6
	s_mov_b32 s2, 0x3f317218
	v_mov_b32_e32 v23, 0x3ecccdef
	v_cndmask_b32_e64 v7, 1.0, 2.0, s[4:5]
	v_mul_f32_e32 v6, v6, v7
	v_add_f32_e32 v9, 1.0, v6
	v_rcp_f32_e32 v14, v9
	v_add_f32_e32 v7, -1.0, v9
	v_sub_f32_e32 v11, v6, v7
	v_add_f32_e32 v7, -1.0, v6
	v_mul_f32_e32 v15, v7, v14
	v_mul_f32_e32 v8, v9, v15
	v_fma_f32 v10, v15, v9, -v8
	v_fmac_f32_e32 v10, v15, v11
	v_add_f32_e32 v6, v8, v10
	v_sub_f32_e32 v9, v7, v6
	v_pk_add_f32 v[12:13], v[6:7], v[8:9] neg_lo:[0,1] neg_hi:[0,1]
	v_mov_b32_e32 v11, v6
	v_pk_add_f32 v[6:7], v[12:13], v[10:11] neg_lo:[0,1] neg_hi:[0,1]
	s_mov_b32 s8, 0x3fb8aa3b
	v_add_f32_e32 v6, v6, v7
	v_add_f32_e32 v6, v9, v6
	v_mul_f32_e32 v7, v14, v6
	v_add_f32_e32 v6, v15, v7
	v_sub_f32_e32 v8, v6, v15
	v_sub_f32_e32 v17, v7, v8
	v_mul_f32_e32 v7, v6, v6
	v_fma_f32 v9, v6, v6, -v7
	v_add_f32_e32 v8, v17, v17
	v_fmac_f32_e32 v9, v6, v8
	v_add_f32_e32 v8, v7, v9
	v_fmamk_f32 v10, v8, 0x3e76c4e1, v22
	v_fmaak_f32 v10, v8, v10, 0x3ecccdef
	v_sub_f32_e32 v7, v8, v7
	v_sub_f32_e32 v18, v9, v7
	v_mul_f32_e32 v7, v8, v10
	v_fma_f32 v9, v8, v10, -v7
	v_fmac_f32_e32 v9, v18, v10
	v_add_f32_e32 v10, v7, v9
	v_add_f32_e32 v11, 0x3f2aaaaa, v10
	v_sub_f32_e32 v7, v10, v7
	v_sub_f32_e32 v7, v9, v7
	v_add_f32_e32 v9, 0xbf2aaaaa, v11
	v_add_f32_e32 v7, 0x31739010, v7
	v_sub_f32_e32 v9, v10, v9
	v_pk_mul_f32 v[12:13], v[6:7], v[8:9]
	v_pk_add_f32 v[14:15], v[6:7], v[8:9]
	v_fma_f32 v10, v8, v6, -v12
	v_fmac_f32_e32 v10, v8, v17
	v_mov_b32_e32 v13, v15
	v_fmac_f32_e32 v10, v18, v6
	v_pk_add_f32 v[8:9], v[12:13], v[10:11]
	v_ldexp_f32 v18, v17, 1
	v_sub_f32_e32 v7, v8, v12
	v_sub_f32_e32 v7, v10, v7
	v_sub_f32_e32 v10, v11, v9
	v_add_f32_e32 v13, v15, v10
	v_pk_mul_f32 v[10:11], v[8:9], v[8:9] op_sel:[0,1] op_sel_hi:[1,0]
	v_cvt_f64_f32_e32 v[14:15], v16
	v_frexp_exp_i32_f64_e32 v11, v[14:15]
	v_subbrev_co_u32_e64 v11, s[4:5], 0, v11, s[4:5]
	v_cvt_f32_i32_e32 v11, v11
	v_fma_f32 v12, v8, v9, -v10
	v_fmac_f32_e32 v12, v8, v13
	v_fmac_f32_e32 v12, v7, v9
	v_mul_f32_e32 v8, 0x3f317218, v11
	v_fma_f32 v14, v11, s2, -v8
	v_fmac_f32_e32 v14, 0xb102e308, v11
	v_ldexp_f32 v15, v6, 1
	v_add_f32_e32 v9, v10, v12
	v_pk_add_f32 v[6:7], v[8:9], v[14:15]
	v_mov_b32_e32 v16, v9
	v_mov_b32_e32 v17, v7
	v_mov_b32_e32 v11, v15
	v_pk_add_f32 v[10:11], v[16:17], v[10:11] neg_lo:[0,1] neg_hi:[0,1]
	v_mov_b32_e32 v13, v9
	v_pk_add_f32 v[10:11], v[12:13], v[10:11] neg_lo:[0,1] neg_hi:[0,1]
	v_mov_b32_e32 v15, v6
	v_add_f32_e32 v9, v18, v10
	v_add_f32_e32 v9, v9, v11
	v_pk_add_f32 v[10:11], v[6:7], v[8:9] neg_lo:[0,1] neg_hi:[0,1]
	v_pk_add_f32 v[12:13], v[6:7], v[8:9]
	v_mov_b32_e32 v8, v9
	v_mov_b32_e32 v11, v13
	v_pk_add_f32 v[16:17], v[14:15], v[10:11] neg_lo:[0,1] neg_hi:[0,1]
	v_pk_add_f32 v[10:11], v[14:15], v[10:11]
	v_mov_b32_e32 v9, v6
	v_pk_add_f32 v[14:15], v[10:11], v[6:7] op_sel:[1,0] op_sel_hi:[0,1] neg_lo:[0,1] neg_hi:[0,1]
	v_pk_add_f32 v[18:19], v[12:13], v[14:15] op_sel_hi:[1,0] neg_lo:[0,1] neg_hi:[0,1]
	v_mov_b32_e32 v10, v13
	v_pk_mov_b32 v[12:13], v[6:7], v[14:15] op_sel:[1,0]
	v_mov_b32_e32 v18, v16
	v_pk_add_f32 v[12:13], v[10:11], v[12:13] neg_lo:[0,1] neg_hi:[0,1]
	v_cmp_eq_f32_e64 s[4:5], 0, v4
	v_pk_add_f32 v[6:7], v[8:9], v[12:13] neg_lo:[0,1] neg_hi:[0,1]
	v_mov_b32_e32 v17, v11
	v_pk_add_f32 v[8:9], v[18:19], v[6:7]
	v_cndmask_b32_e64 v7, v20, 1.0, s[4:5]
	v_frexp_mant_f32_e32 v10, v7
	v_cmp_gt_f32_e64 s[6:7], s1, v10
	s_mov_b32 s1, 0x7f800000
	s_mov_b32 s9, 0xc2ce8ed0
	v_cndmask_b32_e64 v12, 1.0, 2.0, s[6:7]
	v_mul_f32_e32 v10, v10, v12
	v_add_f32_e32 v12, 1.0, v10
	v_rcp_f32_e32 v24, v12
	v_add_f32_e32 v13, -1.0, v12
	v_sub_f32_e32 v15, v10, v13
	v_add_f32_e32 v13, -1.0, v10
	v_mul_f32_e32 v10, v13, v24
	v_mul_f32_e32 v14, v12, v10
	v_fma_f32 v18, v10, v12, -v14
	v_fmac_f32_e32 v18, v10, v15
	v_add_f32_e32 v12, v14, v18
	v_sub_f32_e32 v15, v13, v12
	v_pk_add_f32 v[20:21], v[12:13], v[14:15] neg_lo:[0,1] neg_hi:[0,1]
	v_mov_b32_e32 v19, v12
	v_pk_add_f32 v[12:13], v[20:21], v[18:19] neg_lo:[0,1] neg_hi:[0,1]
	s_movk_i32 s10, 0x204
	v_add_f32_e32 v12, v12, v13
	v_add_f32_e32 v12, v15, v12
	v_mul_f32_e32 v13, v24, v12
	v_add_f32_e32 v12, v10, v13
	v_sub_f32_e32 v10, v12, v10
	v_sub_f32_e32 v10, v13, v10
	v_mul_f32_e32 v13, v12, v12
	v_fma_f32 v15, v12, v12, -v13
	v_add_f32_e32 v14, v10, v10
	v_fmac_f32_e32 v15, v12, v14
	v_add_f32_e32 v14, v13, v15
	v_fmac_f32_e32 v22, 0x3e76c4e1, v14
	v_fmac_f32_e32 v23, v14, v22
	v_sub_f32_e32 v13, v14, v13
	v_sub_f32_e32 v24, v15, v13
	v_mul_f32_e32 v13, v14, v23
	v_fma_f32 v15, v14, v23, -v13
	v_fmac_f32_e32 v15, v24, v23
	v_add_f32_e32 v18, v13, v15
	v_add_f32_e32 v19, 0x3f2aaaaa, v18
	v_sub_f32_e32 v13, v18, v13
	v_sub_f32_e32 v13, v15, v13
	v_add_f32_e32 v15, 0xbf2aaaaa, v19
	v_add_f32_e32 v13, 0x31739010, v13
	v_sub_f32_e32 v15, v18, v15
	v_pk_mul_f32 v[20:21], v[12:13], v[14:15]
	v_pk_add_f32 v[22:23], v[12:13], v[14:15]
	v_fma_f32 v18, v14, v12, -v20
	v_fmac_f32_e32 v18, v14, v10
	v_mov_b32_e32 v21, v23
	v_fmac_f32_e32 v18, v24, v12
	v_pk_add_f32 v[14:15], v[20:21], v[18:19]
	v_and_b32_e32 v62, 0xfc, v1
	v_sub_f32_e32 v13, v14, v20
	v_cvt_f64_f32_e32 v[20:21], v7
	v_frexp_exp_i32_f64_e32 v7, v[20:21]
	v_subbrev_co_u32_e64 v7, s[6:7], 0, v7, s[6:7]
	v_cvt_f32_i32_e32 v7, v7
	v_sub_f32_e32 v13, v18, v13
	v_sub_f32_e32 v18, v19, v15
	v_add_f32_e32 v22, v23, v18
	v_pk_mul_f32 v[18:19], v[14:15], v[14:15] op_sel:[0,1] op_sel_hi:[1,0]
	v_ldexp_f32 v23, v12, 1
	v_fma_f32 v20, v14, v15, -v18
	v_fmac_f32_e32 v20, v14, v22
	v_mul_f32_e32 v14, 0x3f317218, v7
	v_fmac_f32_e32 v20, v13, v15
	v_fma_f32 v22, v7, s2, -v14
	v_fmac_f32_e32 v22, 0xb102e308, v7
	v_add_f32_e32 v15, v18, v20
	v_pk_add_f32 v[12:13], v[14:15], v[22:23]
	v_mov_b32_e32 v24, v15
	v_mov_b32_e32 v25, v13
	v_mov_b32_e32 v19, v23
	v_pk_add_f32 v[18:19], v[24:25], v[18:19] neg_lo:[0,1] neg_hi:[0,1]
	v_mov_b32_e32 v21, v15
	v_ldexp_f32 v7, v10, 1
	v_pk_add_f32 v[18:19], v[20:21], v[18:19] neg_lo:[0,1] neg_hi:[0,1]
	v_mov_b32_e32 v23, v12
	v_add_f32_e32 v7, v7, v18
	v_add_f32_e32 v15, v7, v19
	v_pk_add_f32 v[18:19], v[12:13], v[14:15] neg_lo:[0,1] neg_hi:[0,1]
	v_pk_add_f32 v[20:21], v[12:13], v[14:15]
	v_mov_b32_e32 v14, v15
	v_mov_b32_e32 v19, v21
	v_pk_add_f32 v[24:25], v[22:23], v[18:19] neg_lo:[0,1] neg_hi:[0,1]
	v_pk_add_f32 v[18:19], v[22:23], v[18:19]
	v_mov_b32_e32 v15, v12
	v_pk_add_f32 v[22:23], v[18:19], v[12:13] op_sel:[1,0] op_sel_hi:[0,1] neg_lo:[0,1] neg_hi:[0,1]
	v_pk_add_f32 v[26:27], v[20:21], v[22:23] op_sel_hi:[1,0] neg_lo:[0,1] neg_hi:[0,1]
	v_mov_b32_e32 v18, v21
	v_pk_mov_b32 v[20:21], v[12:13], v[22:23] op_sel:[1,0]
	v_mov_b32_e32 v26, v24
	v_pk_add_f32 v[20:21], v[18:19], v[20:21] neg_lo:[0,1] neg_hi:[0,1]
	v_mov_b32_e32 v23, v9
	v_pk_add_f32 v[12:13], v[14:15], v[20:21] neg_lo:[0,1] neg_hi:[0,1]
	v_mov_b32_e32 v21, v8
	v_pk_add_f32 v[14:15], v[26:27], v[12:13]
	v_mov_b32_e32 v10, v19
	v_mov_b32_e32 v20, v14
	v_mov_b32_e32 v22, v15
	v_pk_add_f32 v[22:23], v[20:21], v[22:23]
	v_mov_b32_e32 v25, v19
	v_pk_add_f32 v[10:11], v[10:11], v[22:23]
	v_mov_b32_e32 v7, v23
	v_mov_b32_e32 v9, v11
	v_mov_b32_e32 v15, v10
	v_pk_add_f32 v[8:9], v[8:9], v[16:17] neg_lo:[0,1] neg_hi:[0,1]
	v_pk_add_f32 v[14:15], v[14:15], v[24:25] neg_lo:[0,1] neg_hi:[0,1]
	v_mov_b32_e32 v19, v8
	v_mov_b32_e32 v18, v14
	v_mov_b32_e32 v13, v22
	v_pk_add_f32 v[6:7], v[6:7], v[8:9] neg_lo:[0,1] neg_hi:[0,1]
	v_pk_add_f32 v[8:9], v[20:21], v[18:19] neg_lo:[0,1] neg_hi:[0,1]
	v_mov_b32_e32 v25, v16
	v_pk_add_f32 v[12:13], v[12:13], v[14:15] neg_lo:[0,1] neg_hi:[0,1]
	v_pk_add_f32 v[8:9], v[24:25], v[8:9] neg_lo:[0,1] neg_hi:[0,1]
	v_mov_b32_e32 v14, v12
	v_mov_b32_e32 v15, v6
	v_pk_add_f32 v[8:9], v[14:15], v[8:9]
	v_mov_b32_e32 v6, v13
	v_pk_add_f32 v[6:7], v[8:9], v[6:7]
	s_mov_b32 s2, 0x42b17218
	v_pk_add_f32 v[8:9], v[10:11], v[6:7]
	v_lshlrev_b32_e32 v28, 2, v62
	v_pk_add_f32 v[10:11], v[8:9], v[10:11] neg_lo:[0,1] neg_hi:[0,1]
	v_lshl_add_u32 v89, v63, 10, 0
	v_pk_add_f32 v[6:7], v[6:7], v[10:11] neg_lo:[0,1] neg_hi:[0,1]
	v_pk_mul_f32 v[10:11], v[4:5], v[8:9]
	v_mov_b32_e32 v65, 0
	v_pk_fma_f32 v[8:9], v[4:5], v[8:9], v[10:11] neg_lo:[0,0,1] neg_hi:[0,0,1]
	v_add_u32_e32 v3, 0, v28
	v_pk_fma_f32 v[6:7], v[4:5], v[6:7], v[8:9]
	v_mul_u32_u24_e32 v29, 0x404, v63
	v_pk_add_f32 v[8:9], v[10:11], v[6:7]
	v_mul_u32_u24_e32 v30, 0x404, v76
	v_pk_add_f32 v[12:13], v[8:9], v[10:11] neg_lo:[0,1] neg_hi:[0,1]
	v_mul_u32_u24_e32 v32, 0x404, v78
	v_pk_add_f32 v[6:7], v[6:7], v[12:13] neg_lo:[0,1] neg_hi:[0,1]
	v_mov_b32_e32 v12, 0x204
	v_cmp_class_f32_e64 s[6:7], v10, v12
	v_mul_u32_u24_e32 v34, 0x404, v80
	v_mul_u32_u24_e32 v36, 0x404, v82
	v_cndmask_b32_e64 v8, v8, v10, s[6:7]
	v_cmp_class_f32_e64 s[6:7], v11, v12
	v_mov_b32_e32 v10, 0x37000000
	s_add_u32 s46, s36, 0x2dc48000
	v_cndmask_b32_e64 v9, v9, v11, s[6:7]
	v_cmp_eq_f32_e64 s[6:7], s2, v9
	v_or_b32_e32 v77, 16, v63
	v_or_b32_e32 v79, 32, v63
	v_cndmask_b32_e64 v11, 0, v10, s[6:7]
	v_sub_f32_e32 v12, v9, v11
	v_mul_f32_e32 v13, 0x3fb8aa3b, v12
	v_fma_f32 v14, v12, s8, -v13
	v_rndne_f32_e32 v15, v13
	v_fmac_f32_e32 v14, 0x32a5705f, v12
	v_sub_f32_e32 v13, v13, v15
	v_add_f32_e32 v13, v13, v14
	v_exp_f32_e32 v13, v13
	v_cvt_i32_f32_e32 v14, v15
	v_cmp_neq_f32_e64 s[6:7], |v9|, s1
	v_or_b32_e32 v81, 48, v63
	s_mov_b32 s41, 0
	v_cndmask_b32_e64 v7, 0, v7, s[6:7]
	v_ldexp_f32 v9, v13, v14
	v_cmp_ngt_f32_e64 s[6:7], s9, v12
	v_add_f32_e32 v7, v11, v7
	v_mov_b32_e32 v11, 0x7f800000
	v_cndmask_b32_e64 v9, 0, v9, s[6:7]
	v_cmp_nlt_f32_e64 s[6:7], s2, v12
	v_or_b32_e32 v85, 0x80, v83
	v_or_b32_e32 v86, 0xffff4000, v190
	v_cndmask_b32_e64 v9, v11, v9, s[6:7]
	v_fma_f32 v7, v9, v7, v9
	v_cmp_class_f32_e64 s[6:7], v9, s10
	v_lshlrev_b32_e32 v66, 8, v63
	v_mov_b32_e32 v67, v65
	v_cndmask_b32_e64 v7, v7, v9, s[6:7]
	v_cmp_neq_f32_e64 s[6:7], v5, |v5|
	s_addc_u32 s47, s37, 0
	v_add_u32_e32 v91, 0xfffffe00, v190
	v_cndmask_b32_e64 v9, v11, 0, s[6:7]
	v_cndmask_b32_e64 v9, v9, 1.0, vcc
	v_cmp_eq_f32_e32 vcc, s2, v8
	v_cmp_class_f32_e64 s[6:7], v5, s10
	s_mov_b32 s33, 0xf400000
	v_cndmask_b32_e32 v5, 0, v10, vcc
	v_cndmask_b32_e64 v87, |v7|, v9, s[6:7]
	v_sub_f32_e32 v7, v8, v5
	v_mul_f32_e32 v9, 0x3fb8aa3b, v7
	v_fma_f32 v10, v7, s8, -v9
	v_rndne_f32_e32 v12, v9
	v_fmac_f32_e32 v10, 0x32a5705f, v7
	v_sub_f32_e32 v9, v9, v12
	v_add_f32_e32 v9, v9, v10
	v_exp_f32_e32 v9, v9
	v_cvt_i32_f32_e32 v10, v12
	v_cmp_neq_f32_e64 vcc, |v8|, s1
	v_cmp_neq_f32_e64 s[6:7], v4, |v4|
	s_movk_i32 s1, 0x300
	v_cndmask_b32_e32 v6, 0, v6, vcc
	v_add_f32_e32 v5, v5, v6
	v_ldexp_f32 v6, v9, v10
	v_cmp_ngt_f32_e32 vcc, s9, v7
	s_mov_b32 s8, 0x31850000
	s_mov_b32 s9, 0x30bd0000
	v_cndmask_b32_e32 v6, 0, v6, vcc
	v_cmp_nlt_f32_e32 vcc, s2, v7
	s_mov_b32 s2, 0xc000
	s_mov_b32 s54, 0xb400000
	v_cndmask_b32_e32 v6, v11, v6, vcc
	v_fma_f32 v5, v6, v5, v6
	v_cmp_class_f32_e64 vcc, v6, s10
	s_mov_b32 s55, 0x8c00000
	s_movk_i32 s56, 0xa8
	v_cndmask_b32_e32 v5, v5, v6, vcc
	v_cndmask_b32_e64 v6, v11, 0, s[6:7]
	v_readlane_b32 s6, v255, 1
	v_cndmask_b32_e64 v6, v6, 1.0, s[4:5]
	v_cmp_class_f32_e64 s[4:5], v4, s10
	v_lshlrev_b32_e32 v4, 11, v63
	v_readlane_b32 s7, v255, 2
	v_cndmask_b32_e64 v88, |v5|, v6, s[4:5]
	v_add3_u32 v90, v89, v4, v28
	s_load_dwordx8 s[16:23], s[6:7], 0x10
	s_load_dwordx2 s[42:43], s[6:7], 0xc8
	s_load_dwordx4 s[24:27], s[6:7], 0xb8
	s_load_dwordx4 s[28:31], s[6:7], 0x40
	s_load_dwordx2 s[44:45], s[6:7], 0x60
	v_lshrrev_b32_e32 v4, 8, v190
	v_mov_b32_e32 v6, 2
	v_mul_hi_u32_u24_e32 v5, 0xc000, v4
	v_mul_u32_u24_e32 v4, 0xc000, v4
	v_lshlrev_b32_sdwa v6, v6, v190 dst_sel:DWORD dst_unused:UNUSED_PAD src0_sel:DWORD src1_sel:BYTE_0
	v_or_b32_e32 v4, v4, v6
	v_lshl_add_u64 v[4:5], s[36:37], 0, v[4:5]
	s_mov_b64 s[6:7], 0x2dc00000
	v_lshl_add_u64 v[68:69], v[4:5], 0, s[6:7]
	s_movk_i32 s6, 0xc00
	v_and_or_b32 v4, v1, s6, v6
	v_add_u32_e32 v4, 0, v4
	v_cmp_gt_u32_e64 s[4:5], s1, v190
	s_movk_i32 s1, 0xff
	v_add_u32_e32 v92, 0x6000, v4
	s_mov_b32 s57, 0x7800000
	v_add_u32_e32 v93, v3, v29
	v_add_u32_e32 v94, v3, v30
	v_add_u32_e32 v95, v3, v31
	v_add_u32_e32 v96, v3, v32
	v_add_u32_e32 v97, v3, v33
	v_add_u32_e32 v98, v3, v34
	v_add_u32_e32 v99, v3, v35
	v_add_u32_e32 v100, v3, v36
	v_lshlrev_b32_e32 v70, 1, v2
	s_mov_b32 s58, 0x2ff50000
	s_mov_b32 s59, 0x2f2d0000
	s_movk_i32 s60, 0x7ff
	s_brev_b32 s61, 18
	s_mov_b32 s62, 0xfe5163ab
	s_mov_b32 s63, 0x3c439041
	s_mov_b32 s64, 0xdb629599
	s_mov_b32 s65, 0xf534ddc0
	s_mov_b32 s66, 0xfc2757d1
	s_mov_b32 s67, 0x4e441529
	s_mov_b32 s68, 0xa2f9836e
	s_mov_b32 s69, 0x3fc90fda
	s_mov_b32 s70, 0x3f22f983
	s_mov_b32 s71, 0xbfc90fda
	v_mov_b32_e32 v101, 0x3c0881c4
	v_mov_b32_e32 v102, 0xbab64f3b
	s_brev_b32 s72, 1
	s_movk_i32 s73, 0x1f8
	s_mov_b32 s74, 0x18000
	s_mov_b32 s75, 0x24000
	s_mov_b32 s76, 0x30000
	s_mov_b32 s77, 0x3c000
	s_mov_b32 s78, 0x48000
	s_mov_b32 s79, 0x54000
	s_mov_b32 s80, 0x60000
	s_mov_b32 s81, 0x6c000
	s_mov_b32 s82, 0x78000
	s_mov_b32 s83, 0x84000
	s_mov_b32 s84, 0x90000
	s_mov_b32 s85, 0x9c000
	s_mov_b32 s86, 0xa8000
	s_mov_b32 s87, 0xb4000
	s_mov_b64 s[48:49], 0x18000
	v_not_b32_e32 v103, 63
	v_not_b32_e32 v104, 31
	v_mov_b32_e32 v105, 0x7fc00000
	v_readlane_b32 s88, v255, 0
	s_mov_b32 s32, 0
	s_movk_i32 s90, 0x2886
	s_cmpk_eq_i32 s3, 0x100
	s_cselect_b32 s93, 1, 0
	s_cmpk_lt_i32 s88, 96
	s_cselect_b32 s94, 1, 0
	s_and_b32 s94, s94, s93
	s_cmp_eq_u32 s94, 1
	s_cselect_b32 s90, 5120, s90
	s_branch .LBB0_27

.Lprep_left_item:
	s_cmpk_lt_i32 s89, 2016
	s_cbranch_scc0 .LBB0_89
	s_mul_i32 s91, s89, 0x2ab
	s_lshr_b32 s91, s91, 16
	s_mul_i32 s92, s91, 96
	s_sub_i32 s92, s89, s92
	s_add_i32 s91, s91, 20
	s_lshl_b32 s91, s91, 8
	s_add_i32 s88, s91, s92
